# attnA: V^T fragment reads issued as early as buffers allow; barrier arrival moved up to before PV MFMA 10
# speedup vs baseline: 1.0072x; 1.0072x over previous
.LBB0_1369:
	s_or_b32 s82, s34, 1
	s_lshl_b64 s[4:5], s[82:83], 7
	s_add_u32 s4, s8, s4
	s_addc_u32 s5, s9, s5
	s_add_u32 m0, s38, 0x8000
	s_nop 0
	global_load_lds_dwordx4 v198, s[4:5]
	s_add_u32 m0, s38, 0x9000
	s_nop 0
	global_load_lds_dwordx4 v199, s[4:5]
	s_add_u32 m0, s38, 0xa000
	s_nop 0
	global_load_lds_dwordx4 v200, s[4:5]
	s_add_u32 m0, s38, 0xb000
	s_nop 0
	global_load_lds_dwordx4 v201, s[4:5]
	v_cmp_lt_i32_e64 s[4:5], s34, v226
	s_and_saveexec_b64 s[22:23], s[4:5]
	s_cbranch_execz .LBB0_1371
	ds_read_b128 v[2:5], v222 offset:24576
	ds_read_b128 v[6:9], v222 offset:28672
	ds_read_b128 v[10:13], v223 offset:24576
	ds_read_b128 v[244:247], v223 offset:28672
	s_waitcnt lgkmcnt(3)
	v_mfma_f32_32x32x16_bf16 v[128:143], v[2:5], v[160:163], v[16:31]
	v_exp_f32_e32 v32, v32
	v_exp_f32_e32 v33, v33
	ds_read_b128 v[2:5], v224 offset:24576
	s_waitcnt lgkmcnt(3)
	v_mfma_f32_32x32x16_bf16 v[144:159], v[6:9], v[160:163], v[16:31]
	v_exp_f32_e32 v34, v34
	v_exp_f32_e32 v35, v35
	ds_read_b128 v[6:9], v224 offset:28672
	s_waitcnt lgkmcnt(3)
	v_mfma_f32_32x32x16_bf16 v[128:143], v[10:13], v[164:167], v[128:143]
	v_exp_f32_e32 v36, v36
	v_exp_f32_e32 v37, v37
	v_add_f32_e32 v0, 0, v32
	ds_read_b128 v[10:13], v225 offset:24576
	s_waitcnt lgkmcnt(3)
	v_mfma_f32_32x32x16_bf16 v[144:159], v[244:247], v[164:167], v[144:159]
	v_exp_f32_e32 v38, v38
	v_exp_f32_e32 v39, v39
	v_add_f32_e32 v0, v33, v0
	ds_read_b128 v[244:247], v225 offset:28672
	s_waitcnt lgkmcnt(3)
	v_mfma_f32_32x32x16_bf16 v[128:143], v[2:5], v[168:171], v[128:143]
	v_cvt_pk_bf16_f32 v208, v32, v33
	v_add_f32_e32 v0, v34, v0
	v_add_f32_e32 v0, v35, v0
	s_waitcnt lgkmcnt(2)
	v_mfma_f32_32x32x16_bf16 v[144:159], v[6:9], v[168:171], v[144:159]
	v_cvt_pk_bf16_f32 v209, v34, v35
	v_add_f32_e32 v0, v36, v0
	v_add_f32_e32 v0, v37, v0
	s_waitcnt lgkmcnt(1)
	v_mfma_f32_32x32x16_bf16 v[128:143], v[10:13], v[172:175], v[128:143]
	v_cvt_pk_bf16_f32 v210, v36, v37
	v_add_f32_e32 v0, v38, v0
	s_waitcnt lgkmcnt(0)
	v_mfma_f32_32x32x16_bf16 v[144:159], v[244:247], v[172:175], v[144:159]
	v_cvt_pk_bf16_f32 v211, v38, v39
	v_add_f32_e32 v0, v39, v0
	s_or_b64 exec, exec, s[22:23]
	v_cmp_le_i32_e32 vcc, s34, v226
	s_and_saveexec_b64 s[22:23], vcc
	ds_read_b64 v[6:7], v228 offset:8192
	ds_read_b64 v[8:9], v229 offset:8192
	ds_read_b64 v[10:11], v230 offset:20480
	ds_read_b64 v[12:13], v231 offset:20480
	ds_read_b64 v[244:245], v230 offset:12288
	ds_read_b64 v[246:247], v231 offset:12288
	ds_read_b64 v[32:33], v230 offset:16384
	ds_read_b64 v[34:35], v231 offset:16384
	ds_read_b64 v[36:37], v232 offset:8192
	ds_read_b64 v[38:39], v233 offset:8192
	s_waitcnt lgkmcnt(8)
	v_mfma_f32_32x32x16_bf16 v[112:127], v[6:9], v[208:211], v[112:127]
	ds_read_b64 v[6:7], v234 offset:20480
	ds_read_b64 v[8:9], v235 offset:20480
	v_exp_f32_e32 v40, v40
	v_exp_f32_e32 v41, v41
	s_waitcnt lgkmcnt(8)
	v_mfma_f32_32x32x16_bf16 v[64:79], v[10:13], v[208:211], v[64:79]
	ds_read_b64 v[10:11], v234 offset:12288
	ds_read_b64 v[12:13], v235 offset:12288
	v_exp_f32_e32 v42, v42
	v_exp_f32_e32 v43, v43
	v_add_f32_e32 v0, v40, v0
	v_add_f32_e32 v0, v41, v0
	s_waitcnt lgkmcnt(8)
	v_mfma_f32_32x32x16_bf16 v[96:111], v[244:247], v[208:211], v[96:111]
	ds_read_b64 v[244:245], v234 offset:16384
	ds_read_b64 v[246:247], v235 offset:16384
	v_exp_f32_e32 v44, v44
	v_exp_f32_e32 v45, v45
	v_add_f32_e32 v0, v42, v0
	v_add_f32_e32 v0, v43, v0
	s_waitcnt lgkmcnt(8)
	v_mfma_f32_32x32x16_bf16 v[80:95], v[32:35], v[208:211], v[80:95]
	ds_read_b64 v[32:33], v236 offset:8192
	ds_read_b64 v[34:35], v237 offset:8192
	v_exp_f32_e32 v46, v46
	v_exp_f32_e32 v47, v47
	v_add_f32_e32 v0, v44, v0
	v_add_f32_e32 v0, v45, v0
	v_add_f32_e32 v0, v46, v0
	v_add_f32_e32 v0, v47, v0
	v_cvt_pk_bf16_f32 v2, v40, v41
	v_cvt_pk_bf16_f32 v3, v42, v43
	v_cvt_pk_bf16_f32 v4, v44, v45
	v_cvt_pk_bf16_f32 v5, v46, v47
	s_nop 1
	ds_read_b64 v[40:41], v238 offset:20480
	ds_read_b64 v[42:43], v239 offset:20480
	ds_read_b64 v[44:45], v238 offset:12288
	ds_read_b64 v[46:47], v239 offset:12288
	s_waitcnt lgkmcnt(12)
	v_mfma_f32_32x32x16_bf16 v[112:127], v[36:39], v[2:5], v[112:127]
	ds_read_b64 v[36:37], v238 offset:16384
	ds_read_b64 v[38:39], v239 offset:16384
	v_exp_f32_e32 v48, v48
	v_exp_f32_e32 v49, v49
	s_waitcnt lgkmcnt(12)
	v_mfma_f32_32x32x16_bf16 v[64:79], v[6:9], v[2:5], v[64:79]
	ds_read_b64 v[6:7], v240 offset:8192
	ds_read_b64 v[8:9], v241 offset:8192
	v_exp_f32_e32 v50, v50
	v_exp_f32_e32 v51, v51
	v_add_f32_e32 v0, v48, v0
	v_add_f32_e32 v0, v49, v0
	s_waitcnt lgkmcnt(12)
	v_mfma_f32_32x32x16_bf16 v[96:111], v[10:13], v[2:5], v[96:111]
	ds_read_b64 v[10:11], v242 offset:12288
	ds_read_b64 v[12:13], v243 offset:12288
	v_exp_f32_e32 v52, v52
	v_exp_f32_e32 v53, v53
	v_add_f32_e32 v0, v50, v0
	v_add_f32_e32 v0, v51, v0
	s_waitcnt lgkmcnt(12)
	v_mfma_f32_32x32x16_bf16 v[80:95], v[244:247], v[2:5], v[80:95]
	ds_read_b64 v[244:245], v242 offset:16384
	ds_read_b64 v[246:247], v243 offset:16384
	v_exp_f32_e32 v54, v54
	v_exp_f32_e32 v55, v55
	v_add_f32_e32 v0, v52, v0
	v_add_f32_e32 v0, v53, v0
	v_add_f32_e32 v0, v54, v0
	v_add_f32_e32 v0, v55, v0
	v_cvt_pk_bf16_f32 v2, v48, v49
	v_cvt_pk_bf16_f32 v3, v50, v51
	v_cvt_pk_bf16_f32 v4, v52, v53
	v_cvt_pk_bf16_f32 v5, v54, v55
	s_nop 1
	ds_read_b64 v[48:49], v242 offset:20480
	ds_read_b64 v[50:51], v243 offset:20480
	s_waitcnt lgkmcnt(14)
	v_mfma_f32_32x32x16_bf16 v[112:127], v[32:35], v[2:5], v[112:127]
	v_exp_f32_e32 v56, v56
	v_exp_f32_e32 v57, v57
	s_waitcnt lgkmcnt(12)
	v_mfma_f32_32x32x16_bf16 v[64:79], v[40:43], v[2:5], v[64:79]
	v_exp_f32_e32 v58, v58
	v_exp_f32_e32 v59, v59
	v_add_f32_e32 v0, v56, v0
	v_add_f32_e32 v0, v57, v0
	s_waitcnt vmcnt(0) lgkmcnt(0)
	s_mov_b64 s[24:25], exec
	s_mov_b64 exec, 1
	v_mov_b32_e32 v248, s33
	v_mov_b32_e32 v249, 1
	ds_add_u32 v248, v249 offset:8
	s_mov_b64 exec, s[24:25]
	s_waitcnt lgkmcnt(10)
	v_mfma_f32_32x32x16_bf16 v[96:111], v[44:47], v[2:5], v[96:111]
	v_exp_f32_e32 v60, v60
	v_exp_f32_e32 v61, v61
	v_add_f32_e32 v0, v58, v0
	v_add_f32_e32 v0, v59, v0
	s_waitcnt lgkmcnt(8)
	v_mfma_f32_32x32x16_bf16 v[80:95], v[36:39], v[2:5], v[80:95]
	v_exp_f32_e32 v62, v62
	v_exp_f32_e32 v63, v63
	v_add_f32_e32 v0, v60, v0
	v_add_f32_e32 v0, v61, v0
	v_add_f32_e32 v0, v62, v0
	v_add_f32_e32 v0, v63, v0
	v_cvt_pk_bf16_f32 v2, v56, v57
	v_cvt_pk_bf16_f32 v3, v58, v59
	v_cvt_pk_bf16_f32 v4, v60, v61
	v_cvt_pk_bf16_f32 v5, v62, v63
	s_nop 1
	s_waitcnt lgkmcnt(6)
	v_mfma_f32_32x32x16_bf16 v[112:127], v[6:9], v[2:5], v[112:127]
	s_waitcnt lgkmcnt(4)
	v_mfma_f32_32x32x16_bf16 v[96:111], v[10:13], v[2:5], v[96:111]
	s_waitcnt lgkmcnt(2)
	v_mfma_f32_32x32x16_bf16 v[80:95], v[244:247], v[2:5], v[80:95]
	s_waitcnt lgkmcnt(0)
	v_mfma_f32_32x32x16_bf16 v[64:79], v[48:51], v[2:5], v[64:79]
	v_add_f32_e32 v227, v227, v0
	s_branch .LBB0_1376
.LBB0_1371:
	s_or_b64 exec, exec, s[22:23]
	v_cmp_le_i32_e32 vcc, s34, v226
	s_and_saveexec_b64 s[22:23], vcc
	s_cbranch_execz .LBB0_1373
	ds_read_b64 v[6:7], v228 offset:8192
	ds_read_b64 v[8:9], v229 offset:8192
	ds_read_b64 v[10:11], v230 offset:20480
	ds_read_b64 v[12:13], v231 offset:20480
	ds_read_b64 v[244:245], v230 offset:12288
	ds_read_b64 v[246:247], v231 offset:12288
	v_exp_f32_e32 v32, v32
	v_exp_f32_e32 v33, v33
	v_exp_f32_e32 v34, v34
	v_exp_f32_e32 v35, v35
	v_exp_f32_e32 v36, v36
	v_exp_f32_e32 v37, v37
	v_exp_f32_e32 v38, v38
	v_exp_f32_e32 v39, v39
	v_cvt_pk_bf16_f32 v2, v32, v33
	v_cvt_pk_bf16_f32 v3, v34, v35
	v_cvt_pk_bf16_f32 v4, v36, v37
	v_cvt_pk_bf16_f32 v5, v38, v39
	v_add_f32_e32 v0, 0, v32
	v_add_f32_e32 v0, v33, v0
	v_add_f32_e32 v0, v34, v0
	v_add_f32_e32 v0, v35, v0
	v_add_f32_e32 v0, v36, v0
	v_add_f32_e32 v0, v37, v0
	v_add_f32_e32 v0, v38, v0
	v_add_f32_e32 v0, v39, v0
	ds_read_b64 v[32:33], v230 offset:16384
	ds_read_b64 v[34:35], v231 offset:16384
	ds_read_b64 v[36:37], v232 offset:8192
	ds_read_b64 v[38:39], v233 offset:8192
	s_waitcnt lgkmcnt(8)
	v_mfma_f32_32x32x16_bf16 v[112:127], v[6:9], v[2:5], v[112:127]
	ds_read_b64 v[6:7], v234 offset:20480
	ds_read_b64 v[8:9], v235 offset:20480
	v_exp_f32_e32 v40, v40
	v_exp_f32_e32 v41, v41
	s_waitcnt lgkmcnt(8)
	v_mfma_f32_32x32x16_bf16 v[64:79], v[10:13], v[2:5], v[64:79]
	ds_read_b64 v[10:11], v234 offset:12288
	ds_read_b64 v[12:13], v235 offset:12288
	v_exp_f32_e32 v42, v42
	v_exp_f32_e32 v43, v43
	v_add_f32_e32 v0, v40, v0
	v_add_f32_e32 v0, v41, v0
	s_waitcnt lgkmcnt(8)
	v_mfma_f32_32x32x16_bf16 v[96:111], v[244:247], v[2:5], v[96:111]
	ds_read_b64 v[244:245], v234 offset:16384
	ds_read_b64 v[246:247], v235 offset:16384
	v_exp_f32_e32 v44, v44
	v_exp_f32_e32 v45, v45
	v_add_f32_e32 v0, v42, v0
	v_add_f32_e32 v0, v43, v0
	s_waitcnt lgkmcnt(8)
	v_mfma_f32_32x32x16_bf16 v[80:95], v[32:35], v[2:5], v[80:95]
	ds_read_b64 v[32:33], v236 offset:8192
	ds_read_b64 v[34:35], v237 offset:8192
	v_exp_f32_e32 v46, v46
	v_exp_f32_e32 v47, v47
	v_add_f32_e32 v0, v44, v0
	v_add_f32_e32 v0, v45, v0
	v_add_f32_e32 v0, v46, v0
	v_add_f32_e32 v0, v47, v0
	v_cvt_pk_bf16_f32 v2, v40, v41
	v_cvt_pk_bf16_f32 v3, v42, v43
	v_cvt_pk_bf16_f32 v4, v44, v45
	v_cvt_pk_bf16_f32 v5, v46, v47
	s_nop 1
	ds_read_b64 v[40:41], v238 offset:20480
	ds_read_b64 v[42:43], v239 offset:20480
	ds_read_b64 v[44:45], v238 offset:12288
	ds_read_b64 v[46:47], v239 offset:12288
	s_waitcnt lgkmcnt(12)
	v_mfma_f32_32x32x16_bf16 v[112:127], v[36:39], v[2:5], v[112:127]
	ds_read_b64 v[36:37], v238 offset:16384
	ds_read_b64 v[38:39], v239 offset:16384
	v_exp_f32_e32 v48, v48
	v_exp_f32_e32 v49, v49
	s_waitcnt lgkmcnt(12)
	v_mfma_f32_32x32x16_bf16 v[64:79], v[6:9], v[2:5], v[64:79]
	ds_read_b64 v[6:7], v240 offset:8192
	ds_read_b64 v[8:9], v241 offset:8192
	v_exp_f32_e32 v50, v50
	v_exp_f32_e32 v51, v51
	v_add_f32_e32 v0, v48, v0
	v_add_f32_e32 v0, v49, v0
	s_waitcnt lgkmcnt(12)
	v_mfma_f32_32x32x16_bf16 v[96:111], v[10:13], v[2:5], v[96:111]
	ds_read_b64 v[10:11], v242 offset:12288
	ds_read_b64 v[12:13], v243 offset:12288
	v_exp_f32_e32 v52, v52
	v_exp_f32_e32 v53, v53
	v_add_f32_e32 v0, v50, v0
	v_add_f32_e32 v0, v51, v0
	s_waitcnt lgkmcnt(12)
	v_mfma_f32_32x32x16_bf16 v[80:95], v[244:247], v[2:5], v[80:95]
	ds_read_b64 v[244:245], v242 offset:16384
	ds_read_b64 v[246:247], v243 offset:16384
	v_exp_f32_e32 v54, v54
	v_exp_f32_e32 v55, v55
	v_add_f32_e32 v0, v52, v0
	v_add_f32_e32 v0, v53, v0
	v_add_f32_e32 v0, v54, v0
	v_add_f32_e32 v0, v55, v0
	v_cvt_pk_bf16_f32 v2, v48, v49
	v_cvt_pk_bf16_f32 v3, v50, v51
	v_cvt_pk_bf16_f32 v4, v52, v53
	v_cvt_pk_bf16_f32 v5, v54, v55
	s_nop 1
	ds_read_b64 v[48:49], v242 offset:20480
	ds_read_b64 v[50:51], v243 offset:20480
	s_waitcnt lgkmcnt(14)
	v_mfma_f32_32x32x16_bf16 v[112:127], v[32:35], v[2:5], v[112:127]
	v_exp_f32_e32 v56, v56
	v_exp_f32_e32 v57, v57
	s_waitcnt lgkmcnt(12)
	v_mfma_f32_32x32x16_bf16 v[64:79], v[40:43], v[2:5], v[64:79]
	v_exp_f32_e32 v58, v58
	v_exp_f32_e32 v59, v59
	v_add_f32_e32 v0, v56, v0
	v_add_f32_e32 v0, v57, v0
	s_waitcnt lgkmcnt(10)
	v_mfma_f32_32x32x16_bf16 v[96:111], v[44:47], v[2:5], v[96:111]
	v_exp_f32_e32 v60, v60
	v_exp_f32_e32 v61, v61
	v_add_f32_e32 v0, v58, v0
	v_add_f32_e32 v0, v59, v0
	s_waitcnt lgkmcnt(8)
	v_mfma_f32_32x32x16_bf16 v[80:95], v[36:39], v[2:5], v[80:95]
	v_exp_f32_e32 v62, v62
	v_exp_f32_e32 v63, v63
	v_add_f32_e32 v0, v60, v0
	v_add_f32_e32 v0, v61, v0
	v_add_f32_e32 v0, v62, v0
	v_add_f32_e32 v0, v63, v0
	v_cvt_pk_bf16_f32 v2, v56, v57
	v_cvt_pk_bf16_f32 v3, v58, v59
	v_cvt_pk_bf16_f32 v4, v60, v61
	v_cvt_pk_bf16_f32 v5, v62, v63
	s_nop 1
	s_waitcnt lgkmcnt(6)
	v_mfma_f32_32x32x16_bf16 v[112:127], v[6:9], v[2:5], v[112:127]
	s_waitcnt lgkmcnt(4)
	v_mfma_f32_32x32x16_bf16 v[96:111], v[10:13], v[2:5], v[96:111]
	s_waitcnt lgkmcnt(2)
	v_mfma_f32_32x32x16_bf16 v[80:95], v[244:247], v[2:5], v[80:95]
	s_waitcnt lgkmcnt(0)
	v_mfma_f32_32x32x16_bf16 v[64:79], v[48:51], v[2:5], v[64:79]
	v_add_f32_e32 v227, v227, v0

.LBB0_1381:
	ds_read_b128 v[2:5], v222
	ds_read_b128 v[6:9], v222 offset:4096
	ds_read_b128 v[10:13], v223
	ds_read_b128 v[244:247], v223 offset:4096
	s_waitcnt lgkmcnt(3)
	v_mfma_f32_32x32x16_bf16 v[32:47], v[2:5], v[160:163], v[16:31]
	v_exp_f32_e32 v128, v128
	v_exp_f32_e32 v129, v129
	ds_read_b128 v[2:5], v224
	s_waitcnt lgkmcnt(3)
	v_mfma_f32_32x32x16_bf16 v[48:63], v[6:9], v[160:163], v[16:31]
	v_exp_f32_e32 v130, v130
	v_exp_f32_e32 v131, v131
	ds_read_b128 v[6:9], v224 offset:4096
	s_waitcnt lgkmcnt(3)
	v_mfma_f32_32x32x16_bf16 v[32:47], v[10:13], v[164:167], v[32:47]
	v_exp_f32_e32 v132, v132
	v_exp_f32_e32 v133, v133
	v_add_f32_e32 v0, 0, v128
	ds_read_b128 v[10:13], v225
	s_waitcnt lgkmcnt(3)
	v_mfma_f32_32x32x16_bf16 v[48:63], v[244:247], v[164:167], v[48:63]
	v_exp_f32_e32 v134, v134
	v_exp_f32_e32 v135, v135
	v_add_f32_e32 v0, v129, v0
	ds_read_b128 v[244:247], v225 offset:4096
	s_waitcnt lgkmcnt(3)
	v_mfma_f32_32x32x16_bf16 v[32:47], v[2:5], v[168:171], v[32:47]
	v_cvt_pk_bf16_f32 v208, v128, v129
	v_add_f32_e32 v0, v130, v0
	v_add_f32_e32 v0, v131, v0
	s_waitcnt lgkmcnt(2)
	v_mfma_f32_32x32x16_bf16 v[48:63], v[6:9], v[168:171], v[48:63]
	v_cvt_pk_bf16_f32 v209, v130, v131
	v_add_f32_e32 v0, v132, v0
	v_add_f32_e32 v0, v133, v0
	s_waitcnt lgkmcnt(1)
	v_mfma_f32_32x32x16_bf16 v[32:47], v[10:13], v[172:175], v[32:47]
	v_cvt_pk_bf16_f32 v210, v132, v133
	v_add_f32_e32 v0, v134, v0
	s_waitcnt lgkmcnt(0)
	v_mfma_f32_32x32x16_bf16 v[48:63], v[244:247], v[172:175], v[48:63]
	v_cvt_pk_bf16_f32 v211, v134, v135
	v_add_f32_e32 v0, v135, v0
	s_or_b64 exec, exec, s[20:21]
	s_and_saveexec_b64 s[20:21], s[4:5]
	ds_read_b64 v[6:7], v228 offset:32768
	ds_read_b64 v[8:9], v229 offset:32768
	ds_read_b64 v[10:11], v230 offset:45056
	ds_read_b64 v[12:13], v231 offset:45056
	ds_read_b64 v[244:245], v230 offset:36864
	ds_read_b64 v[246:247], v231 offset:36864
	ds_read_b64 v[128:129], v230 offset:40960
	ds_read_b64 v[130:131], v231 offset:40960
	ds_read_b64 v[132:133], v232 offset:32768
	ds_read_b64 v[134:135], v233 offset:32768
	s_waitcnt lgkmcnt(8)
	v_mfma_f32_32x32x16_bf16 v[112:127], v[6:9], v[208:211], v[112:127]
	ds_read_b64 v[6:7], v234 offset:45056
	ds_read_b64 v[8:9], v235 offset:45056
	v_exp_f32_e32 v136, v136
	v_exp_f32_e32 v137, v137
	s_waitcnt lgkmcnt(8)
	v_mfma_f32_32x32x16_bf16 v[64:79], v[10:13], v[208:211], v[64:79]
	ds_read_b64 v[10:11], v234 offset:36864
	ds_read_b64 v[12:13], v235 offset:36864
	v_exp_f32_e32 v138, v138
	v_exp_f32_e32 v139, v139
	v_add_f32_e32 v0, v136, v0
	v_add_f32_e32 v0, v137, v0
	s_waitcnt lgkmcnt(8)
	v_mfma_f32_32x32x16_bf16 v[96:111], v[244:247], v[208:211], v[96:111]
	ds_read_b64 v[244:245], v234 offset:40960
	ds_read_b64 v[246:247], v235 offset:40960
	v_exp_f32_e32 v140, v140
	v_exp_f32_e32 v141, v141
	v_add_f32_e32 v0, v138, v0
	v_add_f32_e32 v0, v139, v0
	s_waitcnt lgkmcnt(8)
	v_mfma_f32_32x32x16_bf16 v[80:95], v[128:131], v[208:211], v[80:95]
	ds_read_b64 v[128:129], v236 offset:32768
	ds_read_b64 v[130:131], v237 offset:32768
	v_exp_f32_e32 v142, v142
	v_exp_f32_e32 v143, v143
	v_add_f32_e32 v0, v140, v0
	v_add_f32_e32 v0, v141, v0
	v_add_f32_e32 v0, v142, v0
	v_add_f32_e32 v0, v143, v0
	v_cvt_pk_bf16_f32 v2, v136, v137
	v_cvt_pk_bf16_f32 v3, v138, v139
	v_cvt_pk_bf16_f32 v4, v140, v141
	v_cvt_pk_bf16_f32 v5, v142, v143
	s_nop 1
	ds_read_b64 v[136:137], v238 offset:45056
	ds_read_b64 v[138:139], v239 offset:45056
	ds_read_b64 v[140:141], v238 offset:36864
	ds_read_b64 v[142:143], v239 offset:36864
	s_waitcnt lgkmcnt(12)
	v_mfma_f32_32x32x16_bf16 v[112:127], v[132:135], v[2:5], v[112:127]
	ds_read_b64 v[132:133], v238 offset:40960
	ds_read_b64 v[134:135], v239 offset:40960
	v_exp_f32_e32 v144, v144
	v_exp_f32_e32 v145, v145
	s_waitcnt lgkmcnt(12)
	v_mfma_f32_32x32x16_bf16 v[64:79], v[6:9], v[2:5], v[64:79]
	ds_read_b64 v[6:7], v240 offset:32768
	ds_read_b64 v[8:9], v241 offset:32768
	v_exp_f32_e32 v146, v146
	v_exp_f32_e32 v147, v147
	v_add_f32_e32 v0, v144, v0
	v_add_f32_e32 v0, v145, v0
	s_waitcnt lgkmcnt(12)
	v_mfma_f32_32x32x16_bf16 v[96:111], v[10:13], v[2:5], v[96:111]
	ds_read_b64 v[10:11], v242 offset:36864
	ds_read_b64 v[12:13], v243 offset:36864
	v_exp_f32_e32 v148, v148
	v_exp_f32_e32 v149, v149
	v_add_f32_e32 v0, v146, v0
	v_add_f32_e32 v0, v147, v0
	s_waitcnt lgkmcnt(12)
	v_mfma_f32_32x32x16_bf16 v[80:95], v[244:247], v[2:5], v[80:95]
	ds_read_b64 v[244:245], v242 offset:40960
	ds_read_b64 v[246:247], v243 offset:40960
	v_exp_f32_e32 v150, v150
	v_exp_f32_e32 v151, v151
	v_add_f32_e32 v0, v148, v0
	v_add_f32_e32 v0, v149, v0
	v_add_f32_e32 v0, v150, v0
	v_add_f32_e32 v0, v151, v0
	v_cvt_pk_bf16_f32 v2, v144, v145
	v_cvt_pk_bf16_f32 v3, v146, v147
	v_cvt_pk_bf16_f32 v4, v148, v149
	v_cvt_pk_bf16_f32 v5, v150, v151
	s_nop 1
	ds_read_b64 v[144:145], v242 offset:45056
	ds_read_b64 v[146:147], v243 offset:45056
	s_waitcnt lgkmcnt(14)
	v_mfma_f32_32x32x16_bf16 v[112:127], v[128:131], v[2:5], v[112:127]
	v_exp_f32_e32 v152, v152
	v_exp_f32_e32 v153, v153
	s_waitcnt lgkmcnt(12)
	v_mfma_f32_32x32x16_bf16 v[64:79], v[136:139], v[2:5], v[64:79]
	v_exp_f32_e32 v154, v154
	v_exp_f32_e32 v155, v155
	v_add_f32_e32 v0, v152, v0
	v_add_f32_e32 v0, v153, v0
	s_waitcnt vmcnt(0) lgkmcnt(0)
	s_mov_b64 s[24:25], exec
	s_mov_b64 exec, 1
	v_mov_b32_e32 v248, s33
	v_mov_b32_e32 v249, 1
	ds_add_u32 v248, v249 offset:8
	s_mov_b64 exec, s[24:25]
	s_waitcnt lgkmcnt(10)
	v_mfma_f32_32x32x16_bf16 v[96:111], v[140:143], v[2:5], v[96:111]
	v_exp_f32_e32 v156, v156
	v_exp_f32_e32 v157, v157
	v_add_f32_e32 v0, v154, v0
	v_add_f32_e32 v0, v155, v0
	s_waitcnt lgkmcnt(8)
	v_mfma_f32_32x32x16_bf16 v[80:95], v[132:135], v[2:5], v[80:95]
	v_exp_f32_e32 v158, v158
	v_exp_f32_e32 v159, v159
	v_add_f32_e32 v0, v156, v0
	v_add_f32_e32 v0, v157, v0
	v_add_f32_e32 v0, v158, v0
	v_add_f32_e32 v0, v159, v0
	v_cvt_pk_bf16_f32 v2, v152, v153
	v_cvt_pk_bf16_f32 v3, v154, v155
	v_cvt_pk_bf16_f32 v4, v156, v157
	v_cvt_pk_bf16_f32 v5, v158, v159
	s_nop 1
	s_waitcnt lgkmcnt(6)
	v_mfma_f32_32x32x16_bf16 v[112:127], v[6:9], v[2:5], v[112:127]
	s_waitcnt lgkmcnt(4)
	v_mfma_f32_32x32x16_bf16 v[96:111], v[10:13], v[2:5], v[96:111]
	s_waitcnt lgkmcnt(2)
	v_mfma_f32_32x32x16_bf16 v[80:95], v[244:247], v[2:5], v[80:95]
	s_waitcnt lgkmcnt(0)
	v_mfma_f32_32x32x16_bf16 v[64:79], v[144:147], v[2:5], v[64:79]
	v_add_f32_e32 v227, v0, v227
	s_or_b64 exec, exec, s[20:21]
	s_branch .LBB0_1389

.LBB0_1385:
	ds_read_b64 v[6:7], v228 offset:32768
	ds_read_b64 v[8:9], v229 offset:32768
	ds_read_b64 v[10:11], v230 offset:45056
	ds_read_b64 v[12:13], v231 offset:45056
	ds_read_b64 v[244:245], v230 offset:36864
	ds_read_b64 v[246:247], v231 offset:36864
	v_exp_f32_e32 v128, v128
	v_exp_f32_e32 v129, v129
	v_exp_f32_e32 v130, v130
	v_exp_f32_e32 v131, v131
	v_exp_f32_e32 v132, v132
	v_exp_f32_e32 v133, v133
	v_exp_f32_e32 v134, v134
	v_exp_f32_e32 v135, v135
	v_cvt_pk_bf16_f32 v2, v128, v129
	v_cvt_pk_bf16_f32 v3, v130, v131
	v_cvt_pk_bf16_f32 v4, v132, v133
	v_cvt_pk_bf16_f32 v5, v134, v135
	v_add_f32_e32 v0, 0, v128
	v_add_f32_e32 v0, v129, v0
	v_add_f32_e32 v0, v130, v0
	v_add_f32_e32 v0, v131, v0
	v_add_f32_e32 v0, v132, v0
	v_add_f32_e32 v0, v133, v0
	v_add_f32_e32 v0, v134, v0
	v_add_f32_e32 v0, v135, v0
	ds_read_b64 v[128:129], v230 offset:40960
	ds_read_b64 v[130:131], v231 offset:40960
	ds_read_b64 v[132:133], v232 offset:32768
	ds_read_b64 v[134:135], v233 offset:32768
	s_waitcnt lgkmcnt(8)
	v_mfma_f32_32x32x16_bf16 v[112:127], v[6:9], v[2:5], v[112:127]
	ds_read_b64 v[6:7], v234 offset:45056
	ds_read_b64 v[8:9], v235 offset:45056
	v_exp_f32_e32 v136, v136
	v_exp_f32_e32 v137, v137
	s_waitcnt lgkmcnt(8)
	v_mfma_f32_32x32x16_bf16 v[64:79], v[10:13], v[2:5], v[64:79]
	ds_read_b64 v[10:11], v234 offset:36864
	ds_read_b64 v[12:13], v235 offset:36864
	v_exp_f32_e32 v138, v138
	v_exp_f32_e32 v139, v139
	v_add_f32_e32 v0, v136, v0
	v_add_f32_e32 v0, v137, v0
	s_waitcnt lgkmcnt(8)
	v_mfma_f32_32x32x16_bf16 v[96:111], v[244:247], v[2:5], v[96:111]
	ds_read_b64 v[244:245], v234 offset:40960
	ds_read_b64 v[246:247], v235 offset:40960
	v_exp_f32_e32 v140, v140
	v_exp_f32_e32 v141, v141
	v_add_f32_e32 v0, v138, v0
	v_add_f32_e32 v0, v139, v0
	s_waitcnt lgkmcnt(8)
	v_mfma_f32_32x32x16_bf16 v[80:95], v[128:131], v[2:5], v[80:95]
	ds_read_b64 v[128:129], v236 offset:32768
	ds_read_b64 v[130:131], v237 offset:32768
	v_exp_f32_e32 v142, v142
	v_exp_f32_e32 v143, v143
	v_add_f32_e32 v0, v140, v0
	v_add_f32_e32 v0, v141, v0
	v_add_f32_e32 v0, v142, v0
	v_add_f32_e32 v0, v143, v0
	v_cvt_pk_bf16_f32 v2, v136, v137
	v_cvt_pk_bf16_f32 v3, v138, v139
	v_cvt_pk_bf16_f32 v4, v140, v141
	v_cvt_pk_bf16_f32 v5, v142, v143
	s_nop 1
	ds_read_b64 v[136:137], v238 offset:45056
	ds_read_b64 v[138:139], v239 offset:45056
	ds_read_b64 v[140:141], v238 offset:36864
	ds_read_b64 v[142:143], v239 offset:36864
	s_waitcnt lgkmcnt(12)
	v_mfma_f32_32x32x16_bf16 v[112:127], v[132:135], v[2:5], v[112:127]
	ds_read_b64 v[132:133], v238 offset:40960
	ds_read_b64 v[134:135], v239 offset:40960
	v_exp_f32_e32 v144, v144
	v_exp_f32_e32 v145, v145
	s_waitcnt lgkmcnt(12)
	v_mfma_f32_32x32x16_bf16 v[64:79], v[6:9], v[2:5], v[64:79]
	ds_read_b64 v[6:7], v240 offset:32768
	ds_read_b64 v[8:9], v241 offset:32768
	v_exp_f32_e32 v146, v146
	v_exp_f32_e32 v147, v147
	v_add_f32_e32 v0, v144, v0
	v_add_f32_e32 v0, v145, v0
	s_waitcnt lgkmcnt(12)
	v_mfma_f32_32x32x16_bf16 v[96:111], v[10:13], v[2:5], v[96:111]
	ds_read_b64 v[10:11], v242 offset:36864
	ds_read_b64 v[12:13], v243 offset:36864
	v_exp_f32_e32 v148, v148
	v_exp_f32_e32 v149, v149
	v_add_f32_e32 v0, v146, v0
	v_add_f32_e32 v0, v147, v0
	s_waitcnt lgkmcnt(12)
	v_mfma_f32_32x32x16_bf16 v[80:95], v[244:247], v[2:5], v[80:95]
	ds_read_b64 v[244:245], v242 offset:40960
	ds_read_b64 v[246:247], v243 offset:40960
	v_exp_f32_e32 v150, v150
	v_exp_f32_e32 v151, v151
	v_add_f32_e32 v0, v148, v0
	v_add_f32_e32 v0, v149, v0
	v_add_f32_e32 v0, v150, v0
	v_add_f32_e32 v0, v151, v0
	v_cvt_pk_bf16_f32 v2, v144, v145
	v_cvt_pk_bf16_f32 v3, v146, v147
	v_cvt_pk_bf16_f32 v4, v148, v149
	v_cvt_pk_bf16_f32 v5, v150, v151
	s_nop 1
	ds_read_b64 v[144:145], v242 offset:45056
	ds_read_b64 v[146:147], v243 offset:45056
	s_waitcnt lgkmcnt(14)
	v_mfma_f32_32x32x16_bf16 v[112:127], v[128:131], v[2:5], v[112:127]
	v_exp_f32_e32 v152, v152
	v_exp_f32_e32 v153, v153
	s_waitcnt lgkmcnt(12)
	v_mfma_f32_32x32x16_bf16 v[64:79], v[136:139], v[2:5], v[64:79]
	v_exp_f32_e32 v154, v154
	v_exp_f32_e32 v155, v155
	v_add_f32_e32 v0, v152, v0
	v_add_f32_e32 v0, v153, v0
	s_waitcnt lgkmcnt(10)
	v_mfma_f32_32x32x16_bf16 v[96:111], v[140:143], v[2:5], v[96:111]
	v_exp_f32_e32 v156, v156
	v_exp_f32_e32 v157, v157
	v_add_f32_e32 v0, v154, v0
	v_add_f32_e32 v0, v155, v0
	s_waitcnt lgkmcnt(8)
	v_mfma_f32_32x32x16_bf16 v[80:95], v[132:135], v[2:5], v[80:95]
	v_exp_f32_e32 v158, v158
	v_exp_f32_e32 v159, v159
	v_add_f32_e32 v0, v156, v0
	v_add_f32_e32 v0, v157, v0
	v_add_f32_e32 v0, v158, v0
	v_add_f32_e32 v0, v159, v0
	v_cvt_pk_bf16_f32 v2, v152, v153
	v_cvt_pk_bf16_f32 v3, v154, v155
	v_cvt_pk_bf16_f32 v4, v156, v157
	v_cvt_pk_bf16_f32 v5, v158, v159
	s_nop 1
	s_waitcnt lgkmcnt(6)
	v_mfma_f32_32x32x16_bf16 v[112:127], v[6:9], v[2:5], v[112:127]
	s_waitcnt lgkmcnt(4)
	v_mfma_f32_32x32x16_bf16 v[96:111], v[10:13], v[2:5], v[96:111]
	s_waitcnt lgkmcnt(2)
	v_mfma_f32_32x32x16_bf16 v[80:95], v[244:247], v[2:5], v[80:95]
	s_waitcnt lgkmcnt(0)
	v_mfma_f32_32x32x16_bf16 v[64:79], v[144:147], v[2:5], v[64:79]
	v_add_f32_e32 v227, v0, v227

.LBB0_1411:
	s_or_b32 s82, s31, 1
	s_lshl_b64 s[4:5], s[82:83], 7
	s_add_u32 s4, s8, s4
	s_addc_u32 s5, s9, s5
	s_add_u32 m0, s38, 0x8000
	s_nop 0
	global_load_lds_dwordx4 v196, s[4:5]
	s_add_u32 m0, s38, 0x9000
	s_nop 0
	global_load_lds_dwordx4 v197, s[4:5]
	s_add_u32 m0, s38, 0xa000
	s_nop 0
	global_load_lds_dwordx4 v198, s[4:5]
	s_add_u32 m0, s38, 0xb000
	s_nop 0
	global_load_lds_dwordx4 v199, s[4:5]
	v_cmp_lt_i32_e64 s[4:5], s31, v225
	s_and_saveexec_b64 s[22:23], s[4:5]
	s_cbranch_execz .LBB0_1413
	ds_read_b128 v[2:5], v220 offset:24576
	ds_read_b128 v[6:9], v220 offset:28672
	ds_read_b128 v[10:13], v221 offset:24576
	ds_read_b128 v[244:247], v221 offset:28672
	s_waitcnt lgkmcnt(3)
	v_mfma_f32_32x32x16_bf16 v[128:143], v[2:5], v[160:163], v[16:31]
	v_exp_f32_e32 v80, v80
	v_exp_f32_e32 v81, v81
	ds_read_b128 v[2:5], v222 offset:24576
	s_waitcnt lgkmcnt(3)
	v_mfma_f32_32x32x16_bf16 v[144:159], v[6:9], v[160:163], v[16:31]
	v_exp_f32_e32 v82, v82
	v_exp_f32_e32 v83, v83
	ds_read_b128 v[6:9], v222 offset:28672
	s_waitcnt lgkmcnt(3)
	v_mfma_f32_32x32x16_bf16 v[128:143], v[10:13], v[164:167], v[128:143]
	v_exp_f32_e32 v84, v84
	v_exp_f32_e32 v85, v85
	v_add_f32_e32 v0, 0, v80
	ds_read_b128 v[10:13], v223 offset:24576
	s_waitcnt lgkmcnt(3)
	v_mfma_f32_32x32x16_bf16 v[144:159], v[244:247], v[164:167], v[144:159]
	v_exp_f32_e32 v86, v86
	v_exp_f32_e32 v87, v87
	v_add_f32_e32 v0, v81, v0
	ds_read_b128 v[244:247], v223 offset:28672
	s_waitcnt lgkmcnt(3)
	v_mfma_f32_32x32x16_bf16 v[128:143], v[2:5], v[168:171], v[128:143]
	v_cvt_pk_bf16_f32 v208, v80, v81
	v_add_f32_e32 v0, v82, v0
	v_add_f32_e32 v0, v83, v0
	s_waitcnt lgkmcnt(2)
	v_mfma_f32_32x32x16_bf16 v[144:159], v[6:9], v[168:171], v[144:159]
	v_cvt_pk_bf16_f32 v209, v82, v83
	v_add_f32_e32 v0, v84, v0
	v_add_f32_e32 v0, v85, v0
	s_waitcnt lgkmcnt(1)
	v_mfma_f32_32x32x16_bf16 v[128:143], v[10:13], v[172:175], v[128:143]
	v_cvt_pk_bf16_f32 v210, v84, v85
	v_add_f32_e32 v0, v86, v0
	s_waitcnt lgkmcnt(0)
	v_mfma_f32_32x32x16_bf16 v[144:159], v[244:247], v[172:175], v[144:159]
	v_cvt_pk_bf16_f32 v211, v86, v87
	v_add_f32_e32 v0, v87, v0
	s_or_b64 exec, exec, s[22:23]
	v_cmp_le_i32_e32 vcc, s31, v225
	s_and_saveexec_b64 s[22:23], vcc
	ds_read_b64 v[6:7], v226 offset:8192
	ds_read_b64 v[8:9], v227 offset:8192
	ds_read_b64 v[10:11], v228 offset:20480
	ds_read_b64 v[12:13], v229 offset:20480
	ds_read_b64 v[242:243], v228 offset:12288
	ds_read_b64 v[244:245], v229 offset:12288
	ds_read_b64 v[80:81], v228 offset:16384
	ds_read_b64 v[82:83], v229 offset:16384
	ds_read_b64 v[84:85], v230 offset:8192
	ds_read_b64 v[86:87], v231 offset:8192
	s_waitcnt lgkmcnt(8)
	v_mfma_f32_32x32x16_bf16 v[64:79], v[6:9], v[208:211], v[64:79]
	ds_read_b64 v[6:7], v232 offset:20480
	ds_read_b64 v[8:9], v233 offset:20480
	v_exp_f32_e32 v88, v88
	v_exp_f32_e32 v89, v89
	s_waitcnt lgkmcnt(8)
	v_mfma_f32_32x32x16_bf16 v[112:127], v[10:13], v[208:211], v[112:127]
	ds_read_b64 v[10:11], v232 offset:12288
	ds_read_b64 v[12:13], v233 offset:12288
	v_exp_f32_e32 v90, v90
	v_exp_f32_e32 v91, v91
	v_add_f32_e32 v0, v88, v0
	v_add_f32_e32 v0, v89, v0
	s_waitcnt lgkmcnt(8)
	v_mfma_f32_32x32x16_bf16 v[48:63], v[242:245], v[208:211], v[48:63]
	ds_read_b64 v[242:243], v232 offset:16384
	ds_read_b64 v[244:245], v233 offset:16384
	v_exp_f32_e32 v92, v92
	v_exp_f32_e32 v93, v93
	v_add_f32_e32 v0, v90, v0
	v_add_f32_e32 v0, v91, v0
	s_waitcnt lgkmcnt(8)
	v_mfma_f32_32x32x16_bf16 v[32:47], v[80:83], v[208:211], v[32:47]
	ds_read_b64 v[80:81], v234 offset:8192
	ds_read_b64 v[82:83], v235 offset:8192
	v_exp_f32_e32 v94, v94
	v_exp_f32_e32 v95, v95
	v_add_f32_e32 v0, v92, v0
	v_add_f32_e32 v0, v93, v0
	v_add_f32_e32 v0, v94, v0
	v_add_f32_e32 v0, v95, v0
	v_cvt_pk_bf16_f32 v2, v88, v89
	v_cvt_pk_bf16_f32 v3, v90, v91
	v_cvt_pk_bf16_f32 v4, v92, v93
	v_cvt_pk_bf16_f32 v5, v94, v95
	s_nop 1
	ds_read_b64 v[88:89], v236 offset:20480
	ds_read_b64 v[90:91], v237 offset:20480
	ds_read_b64 v[92:93], v236 offset:12288
	ds_read_b64 v[94:95], v237 offset:12288
	s_waitcnt lgkmcnt(12)
	v_mfma_f32_32x32x16_bf16 v[64:79], v[84:87], v[2:5], v[64:79]
	ds_read_b64 v[84:85], v236 offset:16384
	ds_read_b64 v[86:87], v237 offset:16384
	v_exp_f32_e32 v96, v96
	v_exp_f32_e32 v97, v97
	s_waitcnt lgkmcnt(12)
	v_mfma_f32_32x32x16_bf16 v[112:127], v[6:9], v[2:5], v[112:127]
	ds_read_b64 v[6:7], v238 offset:8192
	ds_read_b64 v[8:9], v239 offset:8192
	v_exp_f32_e32 v98, v98
	v_exp_f32_e32 v99, v99
	v_add_f32_e32 v0, v96, v0
	v_add_f32_e32 v0, v97, v0
	s_waitcnt lgkmcnt(12)
	v_mfma_f32_32x32x16_bf16 v[48:63], v[10:13], v[2:5], v[48:63]
	ds_read_b64 v[10:11], v240 offset:12288
	ds_read_b64 v[12:13], v241 offset:12288
	v_exp_f32_e32 v100, v100
	v_exp_f32_e32 v101, v101
	v_add_f32_e32 v0, v98, v0
	v_add_f32_e32 v0, v99, v0
	s_waitcnt lgkmcnt(12)
	v_mfma_f32_32x32x16_bf16 v[32:47], v[242:245], v[2:5], v[32:47]
	ds_read_b64 v[242:243], v240 offset:16384
	ds_read_b64 v[244:245], v241 offset:16384
	v_exp_f32_e32 v102, v102
	v_exp_f32_e32 v103, v103
	v_add_f32_e32 v0, v100, v0
	v_add_f32_e32 v0, v101, v0
	v_add_f32_e32 v0, v102, v0
	v_add_f32_e32 v0, v103, v0
	v_cvt_pk_bf16_f32 v2, v96, v97
	v_cvt_pk_bf16_f32 v3, v98, v99
	v_cvt_pk_bf16_f32 v4, v100, v101
	v_cvt_pk_bf16_f32 v5, v102, v103
	s_nop 1
	ds_read_b64 v[96:97], v240 offset:20480
	ds_read_b64 v[98:99], v241 offset:20480
	s_waitcnt lgkmcnt(14)
	v_mfma_f32_32x32x16_bf16 v[64:79], v[80:83], v[2:5], v[64:79]
	v_exp_f32_e32 v104, v104
	v_exp_f32_e32 v105, v105
	s_waitcnt lgkmcnt(12)
	v_mfma_f32_32x32x16_bf16 v[112:127], v[88:91], v[2:5], v[112:127]
	v_exp_f32_e32 v106, v106
	v_exp_f32_e32 v107, v107
	v_add_f32_e32 v0, v104, v0
	v_add_f32_e32 v0, v105, v0
	s_waitcnt vmcnt(0) lgkmcnt(0)
	s_mov_b64 s[24:25], exec
	s_mov_b64 exec, 1
	v_mov_b32_e32 v248, s33
	v_mov_b32_e32 v249, 1
	ds_add_u32 v248, v249 offset:8
	s_mov_b64 exec, s[24:25]
	s_waitcnt lgkmcnt(10)
	v_mfma_f32_32x32x16_bf16 v[48:63], v[92:95], v[2:5], v[48:63]
	v_exp_f32_e32 v108, v108
	v_exp_f32_e32 v109, v109
	v_add_f32_e32 v0, v106, v0
	v_add_f32_e32 v0, v107, v0
	s_waitcnt lgkmcnt(8)
	v_mfma_f32_32x32x16_bf16 v[32:47], v[84:87], v[2:5], v[32:47]
	v_exp_f32_e32 v110, v110
	v_exp_f32_e32 v111, v111
	v_add_f32_e32 v0, v108, v0
	v_add_f32_e32 v0, v109, v0
	v_add_f32_e32 v0, v110, v0
	v_add_f32_e32 v0, v111, v0
	v_cvt_pk_bf16_f32 v2, v104, v105
	v_cvt_pk_bf16_f32 v3, v106, v107
	v_cvt_pk_bf16_f32 v4, v108, v109
	v_cvt_pk_bf16_f32 v5, v110, v111
	s_nop 1
	s_waitcnt lgkmcnt(6)
	v_mfma_f32_32x32x16_bf16 v[64:79], v[6:9], v[2:5], v[64:79]
	s_waitcnt lgkmcnt(4)
	v_mfma_f32_32x32x16_bf16 v[48:63], v[10:13], v[2:5], v[48:63]
	s_waitcnt lgkmcnt(2)
	v_mfma_f32_32x32x16_bf16 v[32:47], v[242:245], v[2:5], v[32:47]
	s_waitcnt lgkmcnt(0)
	v_mfma_f32_32x32x16_bf16 v[112:127], v[96:99], v[2:5], v[112:127]
	v_add_f32_e32 v224, v224, v0
	s_branch .LBB0_1418
.LBB0_1413:
	s_or_b64 exec, exec, s[22:23]
	v_cmp_le_i32_e32 vcc, s31, v225
	s_and_saveexec_b64 s[22:23], vcc
	s_cbranch_execz .LBB0_1415
	ds_read_b64 v[6:7], v226 offset:8192
	ds_read_b64 v[8:9], v227 offset:8192
	ds_read_b64 v[10:11], v228 offset:20480
	ds_read_b64 v[12:13], v229 offset:20480
	ds_read_b64 v[242:243], v228 offset:12288
	ds_read_b64 v[244:245], v229 offset:12288
	v_exp_f32_e32 v80, v80
	v_exp_f32_e32 v81, v81
	v_exp_f32_e32 v82, v82
	v_exp_f32_e32 v83, v83
	v_exp_f32_e32 v84, v84
	v_exp_f32_e32 v85, v85
	v_exp_f32_e32 v86, v86
	v_exp_f32_e32 v87, v87
	v_cvt_pk_bf16_f32 v2, v80, v81
	v_cvt_pk_bf16_f32 v3, v82, v83
	v_cvt_pk_bf16_f32 v4, v84, v85
	v_cvt_pk_bf16_f32 v5, v86, v87
	v_add_f32_e32 v0, 0, v80
	v_add_f32_e32 v0, v81, v0
	v_add_f32_e32 v0, v82, v0
	v_add_f32_e32 v0, v83, v0
	v_add_f32_e32 v0, v84, v0
	v_add_f32_e32 v0, v85, v0
	v_add_f32_e32 v0, v86, v0
	v_add_f32_e32 v0, v87, v0
	ds_read_b64 v[80:81], v228 offset:16384
	ds_read_b64 v[82:83], v229 offset:16384
	ds_read_b64 v[84:85], v230 offset:8192
	ds_read_b64 v[86:87], v231 offset:8192
	s_waitcnt lgkmcnt(8)
	v_mfma_f32_32x32x16_bf16 v[64:79], v[6:9], v[2:5], v[64:79]
	ds_read_b64 v[6:7], v232 offset:20480
	ds_read_b64 v[8:9], v233 offset:20480
	v_exp_f32_e32 v88, v88
	v_exp_f32_e32 v89, v89
	s_waitcnt lgkmcnt(8)
	v_mfma_f32_32x32x16_bf16 v[112:127], v[10:13], v[2:5], v[112:127]
	ds_read_b64 v[10:11], v232 offset:12288
	ds_read_b64 v[12:13], v233 offset:12288
	v_exp_f32_e32 v90, v90
	v_exp_f32_e32 v91, v91
	v_add_f32_e32 v0, v88, v0
	v_add_f32_e32 v0, v89, v0
	s_waitcnt lgkmcnt(8)
	v_mfma_f32_32x32x16_bf16 v[48:63], v[242:245], v[2:5], v[48:63]
	ds_read_b64 v[242:243], v232 offset:16384
	ds_read_b64 v[244:245], v233 offset:16384
	v_exp_f32_e32 v92, v92
	v_exp_f32_e32 v93, v93
	v_add_f32_e32 v0, v90, v0
	v_add_f32_e32 v0, v91, v0
	s_waitcnt lgkmcnt(8)
	v_mfma_f32_32x32x16_bf16 v[32:47], v[80:83], v[2:5], v[32:47]
	ds_read_b64 v[80:81], v234 offset:8192
	ds_read_b64 v[82:83], v235 offset:8192
	v_exp_f32_e32 v94, v94
	v_exp_f32_e32 v95, v95
	v_add_f32_e32 v0, v92, v0
	v_add_f32_e32 v0, v93, v0
	v_add_f32_e32 v0, v94, v0
	v_add_f32_e32 v0, v95, v0
	v_cvt_pk_bf16_f32 v2, v88, v89
	v_cvt_pk_bf16_f32 v3, v90, v91
	v_cvt_pk_bf16_f32 v4, v92, v93
	v_cvt_pk_bf16_f32 v5, v94, v95
	s_nop 1
	ds_read_b64 v[88:89], v236 offset:20480
	ds_read_b64 v[90:91], v237 offset:20480
	ds_read_b64 v[92:93], v236 offset:12288
	ds_read_b64 v[94:95], v237 offset:12288
	s_waitcnt lgkmcnt(12)
	v_mfma_f32_32x32x16_bf16 v[64:79], v[84:87], v[2:5], v[64:79]
	ds_read_b64 v[84:85], v236 offset:16384
	ds_read_b64 v[86:87], v237 offset:16384
	v_exp_f32_e32 v96, v96
	v_exp_f32_e32 v97, v97
	s_waitcnt lgkmcnt(12)
	v_mfma_f32_32x32x16_bf16 v[112:127], v[6:9], v[2:5], v[112:127]
	ds_read_b64 v[6:7], v238 offset:8192
	ds_read_b64 v[8:9], v239 offset:8192
	v_exp_f32_e32 v98, v98
	v_exp_f32_e32 v99, v99
	v_add_f32_e32 v0, v96, v0
	v_add_f32_e32 v0, v97, v0
	s_waitcnt lgkmcnt(12)
	v_mfma_f32_32x32x16_bf16 v[48:63], v[10:13], v[2:5], v[48:63]
	ds_read_b64 v[10:11], v240 offset:12288
	ds_read_b64 v[12:13], v241 offset:12288
	v_exp_f32_e32 v100, v100
	v_exp_f32_e32 v101, v101
	v_add_f32_e32 v0, v98, v0
	v_add_f32_e32 v0, v99, v0
	s_waitcnt lgkmcnt(12)
	v_mfma_f32_32x32x16_bf16 v[32:47], v[242:245], v[2:5], v[32:47]
	ds_read_b64 v[242:243], v240 offset:16384
	ds_read_b64 v[244:245], v241 offset:16384
	v_exp_f32_e32 v102, v102
	v_exp_f32_e32 v103, v103
	v_add_f32_e32 v0, v100, v0
	v_add_f32_e32 v0, v101, v0
	v_add_f32_e32 v0, v102, v0
	v_add_f32_e32 v0, v103, v0
	v_cvt_pk_bf16_f32 v2, v96, v97
	v_cvt_pk_bf16_f32 v3, v98, v99
	v_cvt_pk_bf16_f32 v4, v100, v101
	v_cvt_pk_bf16_f32 v5, v102, v103
	s_nop 1
	ds_read_b64 v[96:97], v240 offset:20480
	ds_read_b64 v[98:99], v241 offset:20480
	s_waitcnt lgkmcnt(14)
	v_mfma_f32_32x32x16_bf16 v[64:79], v[80:83], v[2:5], v[64:79]
	v_exp_f32_e32 v104, v104
	v_exp_f32_e32 v105, v105
	s_waitcnt lgkmcnt(12)
	v_mfma_f32_32x32x16_bf16 v[112:127], v[88:91], v[2:5], v[112:127]
	v_exp_f32_e32 v106, v106
	v_exp_f32_e32 v107, v107
	v_add_f32_e32 v0, v104, v0
	v_add_f32_e32 v0, v105, v0
	s_waitcnt lgkmcnt(10)
	v_mfma_f32_32x32x16_bf16 v[48:63], v[92:95], v[2:5], v[48:63]
	v_exp_f32_e32 v108, v108
	v_exp_f32_e32 v109, v109
	v_add_f32_e32 v0, v106, v0
	v_add_f32_e32 v0, v107, v0
	s_waitcnt lgkmcnt(8)
	v_mfma_f32_32x32x16_bf16 v[32:47], v[84:87], v[2:5], v[32:47]
	v_exp_f32_e32 v110, v110
	v_exp_f32_e32 v111, v111
	v_add_f32_e32 v0, v108, v0
	v_add_f32_e32 v0, v109, v0
	v_add_f32_e32 v0, v110, v0
	v_add_f32_e32 v0, v111, v0
	v_cvt_pk_bf16_f32 v2, v104, v105
	v_cvt_pk_bf16_f32 v3, v106, v107
	v_cvt_pk_bf16_f32 v4, v108, v109
	v_cvt_pk_bf16_f32 v5, v110, v111
	s_nop 1
	s_waitcnt lgkmcnt(6)
	v_mfma_f32_32x32x16_bf16 v[64:79], v[6:9], v[2:5], v[64:79]
	s_waitcnt lgkmcnt(4)
	v_mfma_f32_32x32x16_bf16 v[48:63], v[10:13], v[2:5], v[48:63]
	s_waitcnt lgkmcnt(2)
	v_mfma_f32_32x32x16_bf16 v[32:47], v[242:245], v[2:5], v[32:47]
	s_waitcnt lgkmcnt(0)
	v_mfma_f32_32x32x16_bf16 v[112:127], v[96:99], v[2:5], v[112:127]
	v_add_f32_e32 v224, v224, v0

.LBB0_1423:
	ds_read_b128 v[2:5], v220
	ds_read_b128 v[6:9], v220 offset:4096
	ds_read_b128 v[10:13], v221
	ds_read_b128 v[244:247], v221 offset:4096
	s_waitcnt lgkmcnt(3)
	v_mfma_f32_32x32x16_bf16 v[80:95], v[2:5], v[160:163], v[16:31]
	v_exp_f32_e32 v128, v128
	v_exp_f32_e32 v129, v129
	ds_read_b128 v[2:5], v222
	s_waitcnt lgkmcnt(3)
	v_mfma_f32_32x32x16_bf16 v[96:111], v[6:9], v[160:163], v[16:31]
	v_exp_f32_e32 v130, v130
	v_exp_f32_e32 v131, v131
	ds_read_b128 v[6:9], v222 offset:4096
	s_waitcnt lgkmcnt(3)
	v_mfma_f32_32x32x16_bf16 v[80:95], v[10:13], v[164:167], v[80:95]
	v_exp_f32_e32 v132, v132
	v_exp_f32_e32 v133, v133
	v_add_f32_e32 v0, 0, v128
	ds_read_b128 v[10:13], v223
	s_waitcnt lgkmcnt(3)
	v_mfma_f32_32x32x16_bf16 v[96:111], v[244:247], v[164:167], v[96:111]
	v_exp_f32_e32 v134, v134
	v_exp_f32_e32 v135, v135
	v_add_f32_e32 v0, v129, v0
	ds_read_b128 v[244:247], v223 offset:4096
	s_waitcnt lgkmcnt(3)
	v_mfma_f32_32x32x16_bf16 v[80:95], v[2:5], v[168:171], v[80:95]
	v_cvt_pk_bf16_f32 v208, v128, v129
	v_add_f32_e32 v0, v130, v0
	v_add_f32_e32 v0, v131, v0
	s_waitcnt lgkmcnt(2)
	v_mfma_f32_32x32x16_bf16 v[96:111], v[6:9], v[168:171], v[96:111]
	v_cvt_pk_bf16_f32 v209, v130, v131
	v_add_f32_e32 v0, v132, v0
	v_add_f32_e32 v0, v133, v0
	s_waitcnt lgkmcnt(1)
	v_mfma_f32_32x32x16_bf16 v[80:95], v[10:13], v[172:175], v[80:95]
	v_cvt_pk_bf16_f32 v210, v132, v133
	v_add_f32_e32 v0, v134, v0
	s_waitcnt lgkmcnt(0)
	v_mfma_f32_32x32x16_bf16 v[96:111], v[244:247], v[172:175], v[96:111]
	v_cvt_pk_bf16_f32 v211, v134, v135
	v_add_f32_e32 v0, v135, v0
	s_or_b64 exec, exec, s[20:21]
	s_and_saveexec_b64 s[20:21], s[4:5]
	ds_read_b64 v[6:7], v226 offset:32768
	ds_read_b64 v[8:9], v227 offset:32768
	ds_read_b64 v[10:11], v228 offset:45056
	ds_read_b64 v[12:13], v229 offset:45056
	ds_read_b64 v[242:243], v228 offset:36864
	ds_read_b64 v[244:245], v229 offset:36864
	ds_read_b64 v[128:129], v228 offset:40960
	ds_read_b64 v[130:131], v229 offset:40960
	ds_read_b64 v[132:133], v230 offset:32768
	ds_read_b64 v[134:135], v231 offset:32768
	s_waitcnt lgkmcnt(8)
	v_mfma_f32_32x32x16_bf16 v[64:79], v[6:9], v[208:211], v[64:79]
	ds_read_b64 v[6:7], v232 offset:45056
	ds_read_b64 v[8:9], v233 offset:45056
	v_exp_f32_e32 v136, v136
	v_exp_f32_e32 v137, v137
	s_waitcnt lgkmcnt(8)
	v_mfma_f32_32x32x16_bf16 v[112:127], v[10:13], v[208:211], v[112:127]
	ds_read_b64 v[10:11], v232 offset:36864
	ds_read_b64 v[12:13], v233 offset:36864
	v_exp_f32_e32 v138, v138
	v_exp_f32_e32 v139, v139
	v_add_f32_e32 v0, v136, v0
	v_add_f32_e32 v0, v137, v0
	s_waitcnt lgkmcnt(8)
	v_mfma_f32_32x32x16_bf16 v[48:63], v[242:245], v[208:211], v[48:63]
	ds_read_b64 v[242:243], v232 offset:40960
	ds_read_b64 v[244:245], v233 offset:40960
	v_exp_f32_e32 v140, v140
	v_exp_f32_e32 v141, v141
	v_add_f32_e32 v0, v138, v0
	v_add_f32_e32 v0, v139, v0
	s_waitcnt lgkmcnt(8)
	v_mfma_f32_32x32x16_bf16 v[32:47], v[128:131], v[208:211], v[32:47]
	ds_read_b64 v[128:129], v234 offset:32768
	ds_read_b64 v[130:131], v235 offset:32768
	v_exp_f32_e32 v142, v142
	v_exp_f32_e32 v143, v143
	v_add_f32_e32 v0, v140, v0
	v_add_f32_e32 v0, v141, v0
	v_add_f32_e32 v0, v142, v0
	v_add_f32_e32 v0, v143, v0
	v_cvt_pk_bf16_f32 v2, v136, v137
	v_cvt_pk_bf16_f32 v3, v138, v139
	v_cvt_pk_bf16_f32 v4, v140, v141
	v_cvt_pk_bf16_f32 v5, v142, v143
	s_nop 1
	ds_read_b64 v[136:137], v236 offset:45056
	ds_read_b64 v[138:139], v237 offset:45056
	ds_read_b64 v[140:141], v236 offset:36864
	ds_read_b64 v[142:143], v237 offset:36864
	s_waitcnt lgkmcnt(12)
	v_mfma_f32_32x32x16_bf16 v[64:79], v[132:135], v[2:5], v[64:79]
	ds_read_b64 v[132:133], v236 offset:40960
	ds_read_b64 v[134:135], v237 offset:40960
	v_exp_f32_e32 v144, v144
	v_exp_f32_e32 v145, v145
	s_waitcnt lgkmcnt(12)
	v_mfma_f32_32x32x16_bf16 v[112:127], v[6:9], v[2:5], v[112:127]
	ds_read_b64 v[6:7], v238 offset:32768
	ds_read_b64 v[8:9], v239 offset:32768
	v_exp_f32_e32 v146, v146
	v_exp_f32_e32 v147, v147
	v_add_f32_e32 v0, v144, v0
	v_add_f32_e32 v0, v145, v0
	s_waitcnt lgkmcnt(12)
	v_mfma_f32_32x32x16_bf16 v[48:63], v[10:13], v[2:5], v[48:63]
	ds_read_b64 v[10:11], v240 offset:36864
	ds_read_b64 v[12:13], v241 offset:36864
	v_exp_f32_e32 v148, v148
	v_exp_f32_e32 v149, v149
	v_add_f32_e32 v0, v146, v0
	v_add_f32_e32 v0, v147, v0
	s_waitcnt lgkmcnt(12)
	v_mfma_f32_32x32x16_bf16 v[32:47], v[242:245], v[2:5], v[32:47]
	ds_read_b64 v[242:243], v240 offset:40960
	ds_read_b64 v[244:245], v241 offset:40960
	v_exp_f32_e32 v150, v150
	v_exp_f32_e32 v151, v151
	v_add_f32_e32 v0, v148, v0
	v_add_f32_e32 v0, v149, v0
	v_add_f32_e32 v0, v150, v0
	v_add_f32_e32 v0, v151, v0
	v_cvt_pk_bf16_f32 v2, v144, v145
	v_cvt_pk_bf16_f32 v3, v146, v147
	v_cvt_pk_bf16_f32 v4, v148, v149
	v_cvt_pk_bf16_f32 v5, v150, v151
	s_nop 1
	ds_read_b64 v[144:145], v240 offset:45056
	ds_read_b64 v[146:147], v241 offset:45056
	s_waitcnt lgkmcnt(14)
	v_mfma_f32_32x32x16_bf16 v[64:79], v[128:131], v[2:5], v[64:79]
	v_exp_f32_e32 v152, v152
	v_exp_f32_e32 v153, v153
	s_waitcnt lgkmcnt(12)
	v_mfma_f32_32x32x16_bf16 v[112:127], v[136:139], v[2:5], v[112:127]
	v_exp_f32_e32 v154, v154
	v_exp_f32_e32 v155, v155
	v_add_f32_e32 v0, v152, v0
	v_add_f32_e32 v0, v153, v0
	s_waitcnt vmcnt(0) lgkmcnt(0)
	s_mov_b64 s[24:25], exec
	s_mov_b64 exec, 1
	v_mov_b32_e32 v248, s33
	v_mov_b32_e32 v249, 1
	ds_add_u32 v248, v249 offset:8
	s_mov_b64 exec, s[24:25]
	s_waitcnt lgkmcnt(10)
	v_mfma_f32_32x32x16_bf16 v[48:63], v[140:143], v[2:5], v[48:63]
	v_exp_f32_e32 v156, v156
	v_exp_f32_e32 v157, v157
	v_add_f32_e32 v0, v154, v0
	v_add_f32_e32 v0, v155, v0
	s_waitcnt lgkmcnt(8)
	v_mfma_f32_32x32x16_bf16 v[32:47], v[132:135], v[2:5], v[32:47]
	v_exp_f32_e32 v158, v158
	v_exp_f32_e32 v159, v159
	v_add_f32_e32 v0, v156, v0
	v_add_f32_e32 v0, v157, v0
	v_add_f32_e32 v0, v158, v0
	v_add_f32_e32 v0, v159, v0
	v_cvt_pk_bf16_f32 v2, v152, v153
	v_cvt_pk_bf16_f32 v3, v154, v155
	v_cvt_pk_bf16_f32 v4, v156, v157
	v_cvt_pk_bf16_f32 v5, v158, v159
	s_nop 1
	s_waitcnt lgkmcnt(6)
	v_mfma_f32_32x32x16_bf16 v[64:79], v[6:9], v[2:5], v[64:79]
	s_waitcnt lgkmcnt(4)
	v_mfma_f32_32x32x16_bf16 v[48:63], v[10:13], v[2:5], v[48:63]
	s_waitcnt lgkmcnt(2)
	v_mfma_f32_32x32x16_bf16 v[32:47], v[242:245], v[2:5], v[32:47]
	s_waitcnt lgkmcnt(0)
	v_mfma_f32_32x32x16_bf16 v[112:127], v[144:147], v[2:5], v[112:127]
	v_add_f32_e32 v224, v0, v224
	s_or_b64 exec, exec, s[20:21]
	s_branch .LBB0_1431

.LBB0_1427:
	ds_read_b64 v[6:7], v226 offset:32768
	ds_read_b64 v[8:9], v227 offset:32768
	ds_read_b64 v[10:11], v228 offset:45056
	ds_read_b64 v[12:13], v229 offset:45056
	ds_read_b64 v[242:243], v228 offset:36864
	ds_read_b64 v[244:245], v229 offset:36864
	v_exp_f32_e32 v128, v128
	v_exp_f32_e32 v129, v129
	v_exp_f32_e32 v130, v130
	v_exp_f32_e32 v131, v131
	v_exp_f32_e32 v132, v132
	v_exp_f32_e32 v133, v133
	v_exp_f32_e32 v134, v134
	v_exp_f32_e32 v135, v135
	v_cvt_pk_bf16_f32 v2, v128, v129
	v_cvt_pk_bf16_f32 v3, v130, v131
	v_cvt_pk_bf16_f32 v4, v132, v133
	v_cvt_pk_bf16_f32 v5, v134, v135
	v_add_f32_e32 v0, 0, v128
	v_add_f32_e32 v0, v129, v0
	v_add_f32_e32 v0, v130, v0
	v_add_f32_e32 v0, v131, v0
	v_add_f32_e32 v0, v132, v0
	v_add_f32_e32 v0, v133, v0
	v_add_f32_e32 v0, v134, v0
	v_add_f32_e32 v0, v135, v0
	ds_read_b64 v[128:129], v228 offset:40960
	ds_read_b64 v[130:131], v229 offset:40960
	ds_read_b64 v[132:133], v230 offset:32768
	ds_read_b64 v[134:135], v231 offset:32768
	s_waitcnt lgkmcnt(8)
	v_mfma_f32_32x32x16_bf16 v[64:79], v[6:9], v[2:5], v[64:79]
	ds_read_b64 v[6:7], v232 offset:45056
	ds_read_b64 v[8:9], v233 offset:45056
	v_exp_f32_e32 v136, v136
	v_exp_f32_e32 v137, v137
	s_waitcnt lgkmcnt(8)
	v_mfma_f32_32x32x16_bf16 v[112:127], v[10:13], v[2:5], v[112:127]
	ds_read_b64 v[10:11], v232 offset:36864
	ds_read_b64 v[12:13], v233 offset:36864
	v_exp_f32_e32 v138, v138
	v_exp_f32_e32 v139, v139
	v_add_f32_e32 v0, v136, v0
	v_add_f32_e32 v0, v137, v0
	s_waitcnt lgkmcnt(8)
	v_mfma_f32_32x32x16_bf16 v[48:63], v[242:245], v[2:5], v[48:63]
	ds_read_b64 v[242:243], v232 offset:40960
	ds_read_b64 v[244:245], v233 offset:40960
	v_exp_f32_e32 v140, v140
	v_exp_f32_e32 v141, v141
	v_add_f32_e32 v0, v138, v0
	v_add_f32_e32 v0, v139, v0
	s_waitcnt lgkmcnt(8)
	v_mfma_f32_32x32x16_bf16 v[32:47], v[128:131], v[2:5], v[32:47]
	ds_read_b64 v[128:129], v234 offset:32768
	ds_read_b64 v[130:131], v235 offset:32768
	v_exp_f32_e32 v142, v142
	v_exp_f32_e32 v143, v143
	v_add_f32_e32 v0, v140, v0
	v_add_f32_e32 v0, v141, v0
	v_add_f32_e32 v0, v142, v0
	v_add_f32_e32 v0, v143, v0
	v_cvt_pk_bf16_f32 v2, v136, v137
	v_cvt_pk_bf16_f32 v3, v138, v139
	v_cvt_pk_bf16_f32 v4, v140, v141
	v_cvt_pk_bf16_f32 v5, v142, v143
	s_nop 1
	ds_read_b64 v[136:137], v236 offset:45056
	ds_read_b64 v[138:139], v237 offset:45056
	ds_read_b64 v[140:141], v236 offset:36864
	ds_read_b64 v[142:143], v237 offset:36864
	s_waitcnt lgkmcnt(12)
	v_mfma_f32_32x32x16_bf16 v[64:79], v[132:135], v[2:5], v[64:79]
	ds_read_b64 v[132:133], v236 offset:40960
	ds_read_b64 v[134:135], v237 offset:40960
	v_exp_f32_e32 v144, v144
	v_exp_f32_e32 v145, v145
	s_waitcnt lgkmcnt(12)
	v_mfma_f32_32x32x16_bf16 v[112:127], v[6:9], v[2:5], v[112:127]
	ds_read_b64 v[6:7], v238 offset:32768
	ds_read_b64 v[8:9], v239 offset:32768
	v_exp_f32_e32 v146, v146
	v_exp_f32_e32 v147, v147
	v_add_f32_e32 v0, v144, v0
	v_add_f32_e32 v0, v145, v0
	s_waitcnt lgkmcnt(12)
	v_mfma_f32_32x32x16_bf16 v[48:63], v[10:13], v[2:5], v[48:63]
	ds_read_b64 v[10:11], v240 offset:36864
	ds_read_b64 v[12:13], v241 offset:36864
	v_exp_f32_e32 v148, v148
	v_exp_f32_e32 v149, v149
	v_add_f32_e32 v0, v146, v0
	v_add_f32_e32 v0, v147, v0
	s_waitcnt lgkmcnt(12)
	v_mfma_f32_32x32x16_bf16 v[32:47], v[242:245], v[2:5], v[32:47]
	ds_read_b64 v[242:243], v240 offset:40960
	ds_read_b64 v[244:245], v241 offset:40960
	v_exp_f32_e32 v150, v150
	v_exp_f32_e32 v151, v151
	v_add_f32_e32 v0, v148, v0
	v_add_f32_e32 v0, v149, v0
	v_add_f32_e32 v0, v150, v0
	v_add_f32_e32 v0, v151, v0
	v_cvt_pk_bf16_f32 v2, v144, v145
	v_cvt_pk_bf16_f32 v3, v146, v147
	v_cvt_pk_bf16_f32 v4, v148, v149
	v_cvt_pk_bf16_f32 v5, v150, v151
	s_nop 1
	ds_read_b64 v[144:145], v240 offset:45056
	ds_read_b64 v[146:147], v241 offset:45056
	s_waitcnt lgkmcnt(14)
	v_mfma_f32_32x32x16_bf16 v[64:79], v[128:131], v[2:5], v[64:79]
	v_exp_f32_e32 v152, v152
	v_exp_f32_e32 v153, v153
	s_waitcnt lgkmcnt(12)
	v_mfma_f32_32x32x16_bf16 v[112:127], v[136:139], v[2:5], v[112:127]
	v_exp_f32_e32 v154, v154
	v_exp_f32_e32 v155, v155
	v_add_f32_e32 v0, v152, v0
	v_add_f32_e32 v0, v153, v0
	s_waitcnt lgkmcnt(10)
	v_mfma_f32_32x32x16_bf16 v[48:63], v[140:143], v[2:5], v[48:63]
	v_exp_f32_e32 v156, v156
	v_exp_f32_e32 v157, v157
	v_add_f32_e32 v0, v154, v0
	v_add_f32_e32 v0, v155, v0
	s_waitcnt lgkmcnt(8)
	v_mfma_f32_32x32x16_bf16 v[32:47], v[132:135], v[2:5], v[32:47]
	v_exp_f32_e32 v158, v158
	v_exp_f32_e32 v159, v159
	v_add_f32_e32 v0, v156, v0
	v_add_f32_e32 v0, v157, v0
	v_add_f32_e32 v0, v158, v0
	v_add_f32_e32 v0, v159, v0
	v_cvt_pk_bf16_f32 v2, v152, v153
	v_cvt_pk_bf16_f32 v3, v154, v155
	v_cvt_pk_bf16_f32 v4, v156, v157
	v_cvt_pk_bf16_f32 v5, v158, v159
	s_nop 1
	s_waitcnt lgkmcnt(6)
	v_mfma_f32_32x32x16_bf16 v[64:79], v[6:9], v[2:5], v[64:79]
	s_waitcnt lgkmcnt(4)
	v_mfma_f32_32x32x16_bf16 v[48:63], v[10:13], v[2:5], v[48:63]
	s_waitcnt lgkmcnt(2)
	v_mfma_f32_32x32x16_bf16 v[32:47], v[242:245], v[2:5], v[32:47]
	s_waitcnt lgkmcnt(0)
	v_mfma_f32_32x32x16_bf16 v[112:127], v[144:147], v[2:5], v[112:127]
	v_add_f32_e32 v224, v0, v224
